# layer-0 out-proj epilogue: the f32 residual rows of x (last use) loaded non-temporal
# speedup vs baseline: 1.0226x; 1.0081x over previous
.Lo4_prompt:
	s_add_u32 s6, s28, s41
	s_addc_u32 s7, s29, 0
	global_load_dwordx4 v[130:133], v210, s[10:11] offset:0
	global_load_dwordx4 v[134:137], v210, s[10:11] offset:16
	global_load_dwordx4 v[138:141], v210, s[10:11] offset:512
	global_load_dwordx4 v[142:145], v210, s[10:11] offset:528
	s_mov_b64 s[28:29], s[6:7]
	s_mov_b64 s[30:31], s[6:7]
	global_load_dwordx4 v[146:149], v211, s[28:29] offset:0 nt
	global_load_dwordx4 v[150:153], v211, s[28:29] offset:16 nt
	s_add_u32 s28, s28, 0x10000
	s_addc_u32 s29, s29, 0
	global_load_dwordx4 v[154:157], v211, s[28:29] offset:0 nt
	global_load_dwordx4 v[158:161], v211, s[28:29] offset:16 nt
	s_add_u32 s28, s28, 0x10000
	s_addc_u32 s29, s29, 0
	global_load_dwordx4 v[162:165], v211, s[28:29] offset:0 nt
	global_load_dwordx4 v[166:169], v211, s[28:29] offset:16 nt
	s_add_u32 s28, s28, 0x10000
	s_addc_u32 s29, s29, 0
	global_load_dwordx4 v[170:173], v211, s[28:29] offset:0 nt
	global_load_dwordx4 v[174:177], v211, s[28:29] offset:16 nt
	s_add_u32 s28, s28, 0x50000
	s_addc_u32 s29, s29, 0
	global_load_dwordx4 v[178:181], v211, s[30:31] offset:512 nt
	global_load_dwordx4 v[182:185], v211, s[30:31] offset:528 nt
	s_add_u32 s30, s30, 0x10000
	s_addc_u32 s31, s31, 0
	global_load_dwordx4 v[186:189], v211, s[30:31] offset:512 nt
	global_load_dwordx4 v[190:193], v211, s[30:31] offset:528 nt
	s_add_u32 s30, s30, 0x10000
	s_addc_u32 s31, s31, 0
	global_load_dwordx4 v[194:197], v211, s[30:31] offset:512 nt
	global_load_dwordx4 v[198:201], v211, s[30:31] offset:528 nt
	s_add_u32 s30, s30, 0x10000
	s_addc_u32 s31, s31, 0
	global_load_dwordx4 v[202:205], v211, s[30:31] offset:512 nt
	global_load_dwordx4 v[206:209], v211, s[30:31] offset:528 nt
	s_add_u32 s30, s30, 0x50000
	s_addc_u32 s31, s31, 0
	s_waitcnt vmcnt(8)
	v_pk_fma_f32 v[126:127], v[126:127], v[130:131], v[146:147]
	v_pk_fma_f32 v[128:129], v[128:129], v[132:133], v[148:149]
	v_pk_fma_f32 v[122:123], v[122:123], v[134:135], v[150:151]
	v_pk_fma_f32 v[124:125], v[124:125], v[136:137], v[152:153]
	v_pk_fma_f32 v[108:109], v[108:109], v[130:131], v[154:155]
	v_pk_fma_f32 v[110:111], v[110:111], v[132:133], v[156:157]
	v_pk_fma_f32 v[104:105], v[104:105], v[134:135], v[158:159]
	v_pk_fma_f32 v[106:107], v[106:107], v[136:137], v[160:161]
	v_pk_fma_f32 v[92:93], v[92:93], v[130:131], v[162:163]
	v_pk_fma_f32 v[94:95], v[94:95], v[132:133], v[164:165]
	v_pk_fma_f32 v[88:89], v[88:89], v[134:135], v[166:167]
	v_pk_fma_f32 v[90:91], v[90:91], v[136:137], v[168:169]
	v_pk_fma_f32 v[76:77], v[76:77], v[130:131], v[170:171]
	v_pk_fma_f32 v[78:79], v[78:79], v[132:133], v[172:173]
	v_pk_fma_f32 v[72:73], v[72:73], v[134:135], v[174:175]
	v_pk_fma_f32 v[74:75], v[74:75], v[136:137], v[176:177]
	global_load_dwordx4 v[146:149], v211, s[28:29] offset:0 nt
	global_load_dwordx4 v[150:153], v211, s[28:29] offset:16 nt
	s_add_u32 s28, s28, 0x10000
	s_addc_u32 s29, s29, 0
	global_load_dwordx4 v[154:157], v211, s[28:29] offset:0 nt
	global_load_dwordx4 v[158:161], v211, s[28:29] offset:16 nt
	s_add_u32 s28, s28, 0x10000
	s_addc_u32 s29, s29, 0
	global_load_dwordx4 v[162:165], v211, s[28:29] offset:0 nt
	global_load_dwordx4 v[166:169], v211, s[28:29] offset:16 nt
	s_add_u32 s28, s28, 0x10000
	s_addc_u32 s29, s29, 0
	global_load_dwordx4 v[170:173], v211, s[28:29] offset:0 nt
	global_load_dwordx4 v[174:177], v211, s[28:29] offset:16 nt
	s_add_u32 s28, s28, 0x50000
	s_addc_u32 s29, s29, 0
	s_waitcnt vmcnt(8)
	v_pk_fma_f32 v[118:119], v[118:119], v[138:139], v[178:179]
	v_pk_fma_f32 v[120:121], v[120:121], v[140:141], v[180:181]
	v_pk_fma_f32 v[114:115], v[114:115], v[142:143], v[182:183]
	v_pk_fma_f32 v[116:117], v[116:117], v[144:145], v[184:185]
	v_pk_fma_f32 v[100:101], v[100:101], v[138:139], v[186:187]
	v_pk_fma_f32 v[102:103], v[102:103], v[140:141], v[188:189]
	v_pk_fma_f32 v[96:97], v[96:97], v[142:143], v[190:191]
	v_pk_fma_f32 v[98:99], v[98:99], v[144:145], v[192:193]
	v_pk_fma_f32 v[84:85], v[84:85], v[138:139], v[194:195]
	v_pk_fma_f32 v[86:87], v[86:87], v[140:141], v[196:197]
	v_pk_fma_f32 v[80:81], v[80:81], v[142:143], v[198:199]
	v_pk_fma_f32 v[82:83], v[82:83], v[144:145], v[200:201]
	v_pk_fma_f32 v[68:69], v[68:69], v[138:139], v[202:203]
	v_pk_fma_f32 v[70:71], v[70:71], v[140:141], v[204:205]
	v_pk_fma_f32 v[64:65], v[64:65], v[142:143], v[206:207]
	v_pk_fma_f32 v[66:67], v[66:67], v[144:145], v[208:209]
	global_load_dwordx4 v[178:181], v211, s[30:31] offset:512 nt
	global_load_dwordx4 v[182:185], v211, s[30:31] offset:528 nt
	s_add_u32 s30, s30, 0x10000
	s_addc_u32 s31, s31, 0
	global_load_dwordx4 v[186:189], v211, s[30:31] offset:512 nt
	global_load_dwordx4 v[190:193], v211, s[30:31] offset:528 nt
	s_add_u32 s30, s30, 0x10000
	s_addc_u32 s31, s31, 0
	global_load_dwordx4 v[194:197], v211, s[30:31] offset:512 nt
	global_load_dwordx4 v[198:201], v211, s[30:31] offset:528 nt
	s_add_u32 s30, s30, 0x10000
	s_addc_u32 s31, s31, 0
	global_load_dwordx4 v[202:205], v211, s[30:31] offset:512 nt
	global_load_dwordx4 v[206:209], v211, s[30:31] offset:528 nt
	s_add_u32 s30, s30, 0x50000
	s_addc_u32 s31, s31, 0
	v_mul_f32_e32 v236, v127, v127
	v_mul_f32_e32 v237, v129, v129
	v_fmac_f32_e32 v236, v126, v126
	v_fmac_f32_e32 v237, v128, v128
	v_add_f32_e32 v220, v236, v237
	v_mul_f32_e32 v236, v123, v123
	v_mul_f32_e32 v237, v125, v125
	v_fmac_f32_e32 v236, v122, v122
	v_fmac_f32_e32 v237, v124, v124
	v_add_f32_e32 v236, v236, v237
	v_add_f32_e32 v220, v236, v220
	v_mul_f32_e32 v236, v119, v119
	v_mul_f32_e32 v237, v121, v121
	v_fmac_f32_e32 v236, v118, v118
	v_fmac_f32_e32 v237, v120, v120
	v_add_f32_e32 v236, v236, v237
	v_add_f32_e32 v220, v236, v220
	v_mul_f32_e32 v236, v115, v115
	v_mul_f32_e32 v237, v117, v117
	v_fmac_f32_e32 v236, v114, v114
	v_fmac_f32_e32 v237, v116, v116
	v_add_f32_e32 v236, v236, v237
	v_add_f32_e32 v220, v236, v220
	v_mul_f32_e32 v236, v109, v109
	v_mul_f32_e32 v237, v111, v111
	v_fmac_f32_e32 v236, v108, v108
	v_fmac_f32_e32 v237, v110, v110
	v_add_f32_e32 v221, v236, v237
	v_mul_f32_e32 v236, v105, v105
	v_mul_f32_e32 v237, v107, v107
	v_fmac_f32_e32 v236, v104, v104
	v_fmac_f32_e32 v237, v106, v106
	v_add_f32_e32 v236, v236, v237
	v_add_f32_e32 v221, v236, v221
	v_mul_f32_e32 v236, v101, v101
	v_mul_f32_e32 v237, v103, v103
	v_fmac_f32_e32 v236, v100, v100
	v_fmac_f32_e32 v237, v102, v102
	v_add_f32_e32 v236, v236, v237
	v_add_f32_e32 v221, v236, v221
	v_mul_f32_e32 v236, v97, v97
	v_mul_f32_e32 v237, v99, v99
	v_fmac_f32_e32 v236, v96, v96
	v_fmac_f32_e32 v237, v98, v98
	v_add_f32_e32 v236, v236, v237
	v_add_f32_e32 v221, v236, v221
	v_mul_f32_e32 v236, v93, v93
	v_mul_f32_e32 v237, v95, v95
	v_fmac_f32_e32 v236, v92, v92
	v_fmac_f32_e32 v237, v94, v94
	v_add_f32_e32 v222, v236, v237
	v_mul_f32_e32 v236, v89, v89
	v_mul_f32_e32 v237, v91, v91
	v_fmac_f32_e32 v236, v88, v88
	v_fmac_f32_e32 v237, v90, v90
	v_add_f32_e32 v236, v236, v237
	v_add_f32_e32 v222, v236, v222
	v_mul_f32_e32 v236, v85, v85
	v_mul_f32_e32 v237, v87, v87
	v_fmac_f32_e32 v236, v84, v84
	v_fmac_f32_e32 v237, v86, v86
	v_add_f32_e32 v236, v236, v237
	v_add_f32_e32 v222, v236, v222
	v_mul_f32_e32 v236, v81, v81
	v_mul_f32_e32 v237, v83, v83
	v_fmac_f32_e32 v236, v80, v80
	v_fmac_f32_e32 v237, v82, v82
	v_add_f32_e32 v236, v236, v237
	v_add_f32_e32 v222, v236, v222
	v_mul_f32_e32 v236, v77, v77
	v_mul_f32_e32 v237, v79, v79
	v_fmac_f32_e32 v236, v76, v76
	v_fmac_f32_e32 v237, v78, v78
	v_add_f32_e32 v223, v236, v237
	v_mul_f32_e32 v236, v73, v73
	v_mul_f32_e32 v237, v75, v75
	v_fmac_f32_e32 v236, v72, v72
	v_fmac_f32_e32 v237, v74, v74
	v_add_f32_e32 v236, v236, v237
	v_add_f32_e32 v223, v236, v223
	v_mul_f32_e32 v236, v69, v69
	v_mul_f32_e32 v237, v71, v71
	v_fmac_f32_e32 v236, v68, v68
	v_fmac_f32_e32 v237, v70, v70
	v_add_f32_e32 v236, v236, v237
	v_add_f32_e32 v223, v236, v223
	v_mul_f32_e32 v236, v65, v65
	v_mul_f32_e32 v237, v67, v67
	v_fmac_f32_e32 v236, v64, v64
	v_fmac_f32_e32 v237, v66, v66
	v_add_f32_e32 v236, v236, v237
	v_add_f32_e32 v223, v236, v223
	ds_swizzle_b32 v228, v220 offset:swizzle(SWAP,16)
	ds_swizzle_b32 v229, v221 offset:swizzle(SWAP,16)
	ds_swizzle_b32 v230, v222 offset:swizzle(SWAP,16)
	ds_swizzle_b32 v231, v223 offset:swizzle(SWAP,16)
	s_waitcnt lgkmcnt(0)
	v_add_f32_e32 v220, v220, v228
	v_add_f32_e32 v221, v221, v229
	v_add_f32_e32 v222, v222, v230
	v_add_f32_e32 v223, v223, v231
	v_mov_b32_e32 v228, v220
	v_mov_b32_e32 v229, v221
	v_mov_b32_e32 v230, v222
	v_mov_b32_e32 v231, v223
	s_nop 1
	v_permlane32_swap_b32 v228, v220
	v_permlane32_swap_b32 v229, v221
	v_permlane32_swap_b32 v230, v222
	v_permlane32_swap_b32 v231, v223
	s_nop 1
	v_add_f32_e32 v220, v228, v220
	v_add_f32_e32 v221, v229, v221
	v_add_f32_e32 v222, v230, v222
	v_add_f32_e32 v223, v231, v223
	ds_write_b32 v214, v220 offset:0
	ds_write_b32 v214, v221 offset:256
	ds_write_b32 v214, v222 offset:512
	ds_write_b32 v214, v223 offset:768
	s_waitcnt vmcnt(8)
	v_pk_fma_f32 v[60:61], v[60:61], v[130:131], v[146:147]
	v_pk_fma_f32 v[62:63], v[62:63], v[132:133], v[148:149]
	v_pk_fma_f32 v[56:57], v[56:57], v[134:135], v[150:151]
	v_pk_fma_f32 v[58:59], v[58:59], v[136:137], v[152:153]
	v_pk_fma_f32 v[44:45], v[44:45], v[130:131], v[154:155]
	v_pk_fma_f32 v[46:47], v[46:47], v[132:133], v[156:157]
	v_pk_fma_f32 v[40:41], v[40:41], v[134:135], v[158:159]
	v_pk_fma_f32 v[42:43], v[42:43], v[136:137], v[160:161]
	v_pk_fma_f32 v[28:29], v[28:29], v[130:131], v[162:163]
	v_pk_fma_f32 v[30:31], v[30:31], v[132:133], v[164:165]
	v_pk_fma_f32 v[24:25], v[24:25], v[134:135], v[166:167]
	v_pk_fma_f32 v[26:27], v[26:27], v[136:137], v[168:169]
	v_pk_fma_f32 v[12:13], v[12:13], v[130:131], v[170:171]
	v_pk_fma_f32 v[14:15], v[14:15], v[132:133], v[172:173]
	v_pk_fma_f32 v[4:5], v[4:5], v[134:135], v[174:175]
	v_pk_fma_f32 v[6:7], v[6:7], v[136:137], v[176:177]
	s_waitcnt vmcnt(0)
	v_pk_fma_f32 v[52:53], v[52:53], v[138:139], v[178:179]
	v_pk_fma_f32 v[54:55], v[54:55], v[140:141], v[180:181]
	v_pk_fma_f32 v[48:49], v[48:49], v[142:143], v[182:183]
	v_pk_fma_f32 v[50:51], v[50:51], v[144:145], v[184:185]
	v_pk_fma_f32 v[36:37], v[36:37], v[138:139], v[186:187]
	v_pk_fma_f32 v[38:39], v[38:39], v[140:141], v[188:189]
	v_pk_fma_f32 v[32:33], v[32:33], v[142:143], v[190:191]
	v_pk_fma_f32 v[34:35], v[34:35], v[144:145], v[192:193]
	v_pk_fma_f32 v[20:21], v[20:21], v[138:139], v[194:195]
	v_pk_fma_f32 v[22:23], v[22:23], v[140:141], v[196:197]
	v_pk_fma_f32 v[16:17], v[16:17], v[142:143], v[198:199]
	v_pk_fma_f32 v[18:19], v[18:19], v[144:145], v[200:201]
	v_pk_fma_f32 v[8:9], v[8:9], v[138:139], v[202:203]
	v_pk_fma_f32 v[10:11], v[10:11], v[140:141], v[204:205]
	v_pk_fma_f32 v[0:1], v[0:1], v[142:143], v[206:207]
	v_pk_fma_f32 v[2:3], v[2:3], v[144:145], v[208:209]
	v_mul_f32_e32 v236, v61, v61
	v_mul_f32_e32 v237, v63, v63
	v_fmac_f32_e32 v236, v60, v60
	v_fmac_f32_e32 v237, v62, v62
	v_add_f32_e32 v224, v236, v237
	v_mul_f32_e32 v236, v57, v57
	v_mul_f32_e32 v237, v59, v59
	v_fmac_f32_e32 v236, v56, v56
	v_fmac_f32_e32 v237, v58, v58
	v_add_f32_e32 v236, v236, v237
	v_add_f32_e32 v224, v236, v224
	v_mul_f32_e32 v236, v53, v53
	v_mul_f32_e32 v237, v55, v55
	v_fmac_f32_e32 v236, v52, v52
	v_fmac_f32_e32 v237, v54, v54
	v_add_f32_e32 v236, v236, v237
	v_add_f32_e32 v224, v236, v224
	v_mul_f32_e32 v236, v49, v49
	v_mul_f32_e32 v237, v51, v51
	v_fmac_f32_e32 v236, v48, v48
	v_fmac_f32_e32 v237, v50, v50
	v_add_f32_e32 v236, v236, v237
	v_add_f32_e32 v224, v236, v224
	v_mul_f32_e32 v236, v45, v45
	v_mul_f32_e32 v237, v47, v47
	v_fmac_f32_e32 v236, v44, v44
	v_fmac_f32_e32 v237, v46, v46
	v_add_f32_e32 v225, v236, v237
	v_mul_f32_e32 v236, v41, v41
	v_mul_f32_e32 v237, v43, v43
	v_fmac_f32_e32 v236, v40, v40
	v_fmac_f32_e32 v237, v42, v42
	v_add_f32_e32 v236, v236, v237
	v_add_f32_e32 v225, v236, v225
	v_mul_f32_e32 v236, v37, v37
	v_mul_f32_e32 v237, v39, v39
	v_fmac_f32_e32 v236, v36, v36
	v_fmac_f32_e32 v237, v38, v38
	v_add_f32_e32 v236, v236, v237
	v_add_f32_e32 v225, v236, v225
	v_mul_f32_e32 v236, v33, v33
	v_mul_f32_e32 v237, v35, v35
	v_fmac_f32_e32 v236, v32, v32
	v_fmac_f32_e32 v237, v34, v34
	v_add_f32_e32 v236, v236, v237
	v_add_f32_e32 v225, v236, v225
	v_mul_f32_e32 v236, v29, v29
	v_mul_f32_e32 v237, v31, v31
	v_fmac_f32_e32 v236, v28, v28
	v_fmac_f32_e32 v237, v30, v30
	v_add_f32_e32 v226, v236, v237
	v_mul_f32_e32 v236, v25, v25
	v_mul_f32_e32 v237, v27, v27
	v_fmac_f32_e32 v236, v24, v24
	v_fmac_f32_e32 v237, v26, v26
	v_add_f32_e32 v236, v236, v237
	v_add_f32_e32 v226, v236, v226
	v_mul_f32_e32 v236, v21, v21
	v_mul_f32_e32 v237, v23, v23
	v_fmac_f32_e32 v236, v20, v20
	v_fmac_f32_e32 v237, v22, v22
	v_add_f32_e32 v236, v236, v237
	v_add_f32_e32 v226, v236, v226
	v_mul_f32_e32 v236, v17, v17
	v_mul_f32_e32 v237, v19, v19
	v_fmac_f32_e32 v236, v16, v16
	v_fmac_f32_e32 v237, v18, v18
	v_add_f32_e32 v236, v236, v237
	v_add_f32_e32 v226, v236, v226
	v_mul_f32_e32 v236, v13, v13
	v_mul_f32_e32 v237, v15, v15
	v_fmac_f32_e32 v236, v12, v12
	v_fmac_f32_e32 v237, v14, v14
	v_add_f32_e32 v227, v236, v237
	v_mul_f32_e32 v236, v5, v5
	v_mul_f32_e32 v237, v7, v7
	v_fmac_f32_e32 v236, v4, v4
	v_fmac_f32_e32 v237, v6, v6
	v_add_f32_e32 v236, v236, v237
	v_add_f32_e32 v227, v236, v227
	v_mul_f32_e32 v236, v9, v9
	v_mul_f32_e32 v237, v11, v11
	v_fmac_f32_e32 v236, v8, v8
	v_fmac_f32_e32 v237, v10, v10
	v_add_f32_e32 v236, v236, v237
	v_add_f32_e32 v227, v236, v227
	v_mul_f32_e32 v236, v1, v1
	v_mul_f32_e32 v237, v3, v3
	v_fmac_f32_e32 v236, v0, v0
	v_fmac_f32_e32 v237, v2, v2
	v_add_f32_e32 v236, v236, v237
	v_add_f32_e32 v227, v236, v227
	ds_swizzle_b32 v232, v224 offset:swizzle(SWAP,16)
	ds_swizzle_b32 v233, v225 offset:swizzle(SWAP,16)
	ds_swizzle_b32 v234, v226 offset:swizzle(SWAP,16)
	ds_swizzle_b32 v235, v227 offset:swizzle(SWAP,16)
	s_waitcnt lgkmcnt(0)
	v_add_f32_e32 v224, v224, v232
	v_add_f32_e32 v225, v225, v233
	v_add_f32_e32 v226, v226, v234
	v_add_f32_e32 v227, v227, v235
	v_mov_b32_e32 v232, v224
	v_mov_b32_e32 v233, v225
	v_mov_b32_e32 v234, v226
	v_mov_b32_e32 v235, v227
	s_nop 1
	v_permlane32_swap_b32 v232, v224
	v_permlane32_swap_b32 v233, v225
	v_permlane32_swap_b32 v234, v226
	v_permlane32_swap_b32 v235, v227
	s_nop 1
	v_add_f32_e32 v224, v232, v224
	v_add_f32_e32 v225, v233, v225
	v_add_f32_e32 v226, v234, v226
	v_add_f32_e32 v227, v235, v227
	ds_write_b32 v214, v224 offset:2048
	ds_write_b32 v214, v225 offset:2304
	ds_write_b32 v214, v226 offset:2560
	ds_write_b32 v214, v227 offset:2816
	s_lshl_b32 s41, s39, 12
	s_lshl_b32 s28, s74, 10
	s_add_u32 s41, s41, s28
	s_lshl_b32 s28, s35, 1
	s_add_u32 s41, s41, s28
	s_add_u32 s41, s41, 0xb0000
	s_add_u32 s6, s4, s41
	s_addc_u32 s7, s5, 0
